# attention phase: the 20 K-fragment LDS reads of each 16-query group hoisted to the top of the group body (fresh VGPRs, counted lgkmcnt)
# baseline (speedup 1.0000x reference)
; #define LAS __attribute__((address_space(3)))
; __device__ __forceinline__ unsigned pk2(float lo, float hi) { return f2bf(lo) | (f2bf(hi) << 16); }
; __device__ __forceinline__ float bflo(unsigned w) { return __uint_as_float(w << 16); }
; __device__ __forceinline__ float bfhi(unsigned w) { return __uint_as_float(w & 0xffff0000u); }
; #define ATT_LOAD_Q(A) do { const size_t qrw_ = qrow0 + (A) * 16; const bf16* qp_ = QKV + qrw_ * QKVW + (qrw_ >> 8) * adjq + qh * 64 + fq * 8; qw0 = *(const u32x4*)qp_; qw1 = *(const u32x4*)(qp_ + 32); \
;         const f32x4* rp_ = (const f32x4*)(rope + (size_t)(nb * 128 + (A) * 16 + fr) * 16); _Pragma("unroll") for (int c = 0; c < 4; ++c) qr[c] = rp_[c]; } while (0)
; __device__ __forceinline__ void attn_phase(LAS unsigned char* lds, const bf16* QKV, bf16* O, const float* rope, const float* sinks) {
;     ...
;             { u32x4 w0 = qw0; const u32x4 w1 = qw1;
;               const float cs[8] = {qr[0][0], qr[0][2], qr[1][0], qr[1][2], qr[2][0], qr[2][2], qr[3][0], qr[3][2]}, sn[8] = {qr[0][1], qr[0][3], qr[1][1], qr[1][3], qr[2][1], qr[2][3], qr[3][1], qr[3][3]};
;               u32x4 pw; pw.x = __shfl_xor(w0.x, 16); pw.y = __shfl_xor(w0.y, 16); pw.z = __shfl_xor(w0.z, 16); pw.w = __shfl_xor(w0.w, 16);
;               const float sg = fq == 0 ? -1.f : 1.f;
;               u32x4 rw;
; #pragma unroll
;               for (int e = 0; e < 4; ++e) { const float xa = bflo(w0[e]), xb = bfhi(w0[e]), pa = bflo(pw[e]), pb = bfhi(pw[e]);
;                   rw[e] = pk2(xa * cs[2 * e] + sg * pa * sn[2 * e], xb * cs[2 * e + 1] + sg * pb * sn[2 * e + 1]); }
;               if (fq < 2) w0 = rw;
;               qf[0] = __builtin_bit_cast(bf16x8, w0); qf[1] = __builtin_bit_cast(bf16x8, w1); }
;             if (a < 7) ATT_LOAD_Q(a + 1);
;             f32x4 sc[10];
; #pragma unroll
;             for (int j = 0; j < 10; ++j) { const LAS bf16* kp = Kl + ((a + j) * 16 + fr) * KP + fq * 8;
;                 f32x4 z = (f32x4){0.f, 0.f, 0.f, 0.f};
;                 z = __builtin_amdgcn_mfma_f32_16x16x32_bf16(*(const LAS bf16x8*)kp, qf[0], z, 0, 0, 0);
;                 z = __builtin_amdgcn_mfma_f32_16x16x32_bf16(*(const LAS bf16x8*)(kp + 32), qf[1], z, 0, 0, 0);
;                 sc[j] = z; }
.LBB0_1748:
	s_waitcnt lgkmcnt(2)
	v_lshlrev_b32_e32 v133, 16, v127
	v_lshlrev_b32_e32 v132, 16, v126
	v_and_b32_e32 v127, 0xffff0000, v127
	v_and_b32_e32 v126, 0xffff0000, v126
	v_mov_b32_e32 v135, v92
	v_mov_b32_e32 v92, v97
	v_mov_b32_e32 v97, v94
	v_pk_mul_f32 v[126:127], v[104:105], v[126:127]
	v_mov_b32_e32 v94, v99
	v_and_b32_e32 v131, 0xffff0000, v81
	v_and_b32_e32 v130, 0xffff0000, v80
	v_mov_b32_e32 v134, v96
	v_pk_mul_f32 v[132:133], v[104:105], v[132:133]
	v_mov_b32_e32 v96, v98
	v_pk_mul_f32 v[94:95], v[94:95], v[126:127]
	s_waitcnt lgkmcnt(0)
	v_or_b32_e32 v165, s28, v34
	v_mad_u64_u32 v[166:167], s[100:101], v165, s42, v[106:107]
	ds_read_b128 v[168:171], v166 offset:0
	ds_read_b128 v[172:175], v166 offset:64
	ds_read_b128 v[176:179], v166 offset:2304
	ds_read_b128 v[180:183], v166 offset:2368
	ds_read_b128 v[184:187], v166 offset:4608
	ds_read_b128 v[188:191], v166 offset:4672
	ds_read_b128 v[192:195], v166 offset:6912
	ds_read_b128 v[196:199], v166 offset:6976
	ds_read_b128 v[202:205], v166 offset:9216
	ds_read_b128 v[206:209], v166 offset:9280
	ds_read_b128 v[210:213], v166 offset:11520
	ds_read_b128 v[214:217], v166 offset:11584
	ds_read_b128 v[218:221], v166 offset:13824
	ds_read_b128 v[222:225], v166 offset:13888
	ds_read_b128 v[226:229], v166 offset:16128
	ds_read_b128 v[230:233], v166 offset:16192
	ds_read_b128 v[234:237], v166 offset:18432
	ds_read_b128 v[238:241], v166 offset:18496
	ds_read_b128 v[242:245], v166 offset:20736
	ds_read_b128 v[246:249], v166 offset:20800
	v_lshlrev_b32_e32 v127, 16, v125
	v_lshlrev_b32_e32 v126, 16, v115
	v_lshlrev_b32_e32 v129, 16, v81
	v_lshlrev_b32_e32 v128, 16, v80
	v_pk_mul_f32 v[92:93], v[92:93], v[132:133]
	v_pk_fma_f32 v[94:95], v[96:97], v[130:131], v[94:95]
	v_mov_b32_e32 v131, v84
	v_pk_mul_f32 v[126:127], v[104:105], v[126:127]
	v_mov_b32_e32 v84, v89
	v_pk_fma_f32 v[92:93], v[134:135], v[128:129], v[92:93]
	v_lshlrev_b32_e32 v97, 16, v83
	v_lshlrev_b32_e32 v96, 16, v82
	v_and_b32_e32 v129, 0xffff0000, v125
	v_and_b32_e32 v128, 0xffff0000, v115
	v_mov_b32_e32 v130, v88
	v_pk_mul_f32 v[84:85], v[84:85], v[126:127]
	v_mov_b32_e32 v89, v86
	v_pk_fma_f32 v[84:85], v[130:131], v[96:97], v[84:85]
	v_pk_mul_f32 v[96:97], v[104:105], v[128:129]
	v_mov_b32_e32 v86, v91
	v_and_b32_e32 v99, 0xffff0000, v83
	v_and_b32_e32 v98, 0xffff0000, v82
	v_mov_b32_e32 v88, v90
	v_pk_mul_f32 v[86:87], v[86:87], v[96:97]
	v_or_b32_e32 v113, s28, v34
	v_pk_fma_f32 v[86:87], v[88:89], v[98:99], v[86:87]
	v_bfe_u32 v88, v94, 16, 1
	v_bfe_u32 v89, v95, 16, 1
	v_bfe_u32 v90, v86, 16, 1
	v_bfe_u32 v91, v87, 16, 1
	v_add3_u32 v90, v86, v90, s39
	v_add3_u32 v95, v95, v89, s39
	v_add3_u32 v86, v94, v88, s39
	v_bfe_u32 v88, v84, 16, 1
	v_bfe_u32 v89, v93, 16, 1
	v_bfe_u32 v94, v92, 16, 1
	v_add3_u32 v91, v87, v91, s39
	v_bfe_u32 v87, v85, 16, 1
	v_add3_u32 v92, v92, v94, s39
	v_add3_u32 v89, v93, v89, s39
	v_add3_u32 v84, v84, v88, s39
	v_add3_u32 v85, v85, v87, s39
	v_lshrrev_b32_e32 v94, 16, v84
	v_lshrrev_b32_e32 v96, 16, v89
	v_lshrrev_b32_e32 v84, 16, v92
	v_mad_u64_u32 v[88:89], s[18:19], v113, s42, v[106:107]
	v_lshrrev_b32_e32 v93, 16, v85
	v_and_or_b32 v92, v86, s38, v84
	v_and_or_b32 v89, v95, s38, v96
	v_and_or_b32 v90, v90, s38, v94
	v_and_or_b32 v91, v91, s38, v93
	v_cndmask_b32_e64 v95, v83, v91, s[8:9]
	v_cndmask_b32_e64 v94, v82, v90, s[8:9]
	v_cndmask_b32_e64 v93, v81, v89, s[8:9]
	v_cndmask_b32_e64 v92, v80, v92, s[8:9]
	s_add_i32 s45, s50, 1
	s_lshl_b32 s54, s45, 4
	v_or_b32_e32 v88, s54, v34
	v_mad_u64_u32 v[126:127], s[18:19], v88, s42, v[106:107]
	s_waitcnt lgkmcnt(15)
	v_mfma_f32_16x16x32_bf16 v[84:87], v[168:171], v[92:95], 0
	s_add_i32 s49, s28, 32
	s_add_i32 s56, s28, 48
	s_waitcnt lgkmcnt(15)
	v_mfma_f32_16x16x32_bf16 v[96:99], v[172:175], v[76:79], v[84:87]
	s_add_i32 s48, s28, 64
	s_add_i32 s53, s28, 0x50
	s_waitcnt lgkmcnt(15)
	v_mfma_f32_16x16x32_bf16 v[84:87], v[176:179], v[92:95], 0
	v_or_b32_e32 v88, s56, v34
	v_mad_u64_u32 v[134:135], s[18:19], v88, s42, v[106:107]
	s_waitcnt lgkmcnt(15)
	v_mfma_f32_16x16x32_bf16 v[126:129], v[180:183], v[76:79], v[84:87]
	v_or_b32_e32 v80, s49, v34
	s_add_i32 s47, s28, 0x60
	s_add_i32 s52, s28, 0x70
	s_nop 0
	v_mad_u64_u32 v[84:85], s[18:19], v80, s42, v[106:107]
	s_waitcnt lgkmcnt(15)
	v_mfma_f32_16x16x32_bf16 v[80:83], v[184:187], v[92:95], 0
	s_add_i32 s46, s28, 0x80
	s_add_i32 s51, s28, 0x90
	s_waitcnt lgkmcnt(14)
	v_mfma_f32_16x16x32_bf16 v[130:133], v[188:191], v[76:79], v[80:83]
	v_or_b32_e32 v115, s51, v34
	v_mad_u64_u32 v[154:155], s[18:19], v115, s42, v[106:107]
	s_nop 0
	s_waitcnt lgkmcnt(13)
	v_mfma_f32_16x16x32_bf16 v[84:87], v[192:195], v[92:95], 0
	v_or_b32_e32 v88, s53, v34
	v_mad_u64_u32 v[142:143], s[18:19], v88, s42, v[106:107]
	s_waitcnt lgkmcnt(12)
	v_mfma_f32_16x16x32_bf16 v[134:137], v[196:199], v[76:79], v[84:87]
	v_or_b32_e32 v80, s48, v34
	s_nop 2
	v_mad_u64_u32 v[84:85], s[18:19], v80, s42, v[106:107]
	s_waitcnt lgkmcnt(11)
	v_mfma_f32_16x16x32_bf16 v[80:83], v[202:205], v[92:95], 0
	v_mul_f32_e32 v115, 0x3e000000, v127
	v_mul_f32_e32 v127, 0x3e000000, v130
	s_waitcnt lgkmcnt(10)
	v_mfma_f32_16x16x32_bf16 v[138:141], v[206:209], v[76:79], v[80:83]
	v_or_b32_e32 v130, s56, v108
	s_nop 1
	s_waitcnt lgkmcnt(9)
	v_mfma_f32_16x16x32_bf16 v[84:87], v[210:213], v[92:95], 0
	v_or_b32_e32 v88, s52, v34
	v_mad_u64_u32 v[150:151], s[18:19], v88, s42, v[106:107]
	s_waitcnt lgkmcnt(8)
	v_mfma_f32_16x16x32_bf16 v[142:145], v[214:217], v[76:79], v[84:87]
	v_or_b32_e32 v80, s47, v34
	s_nop 2
	v_mad_u64_u32 v[84:85], s[18:19], v80, s42, v[106:107]
	s_waitcnt lgkmcnt(7)
	v_mfma_f32_16x16x32_bf16 v[80:83], v[218:221], v[92:95], 0
	s_waitcnt lgkmcnt(6)
; #define LAS __attribute__((address_space(3)))
; __device__ __forceinline__ void attn_phase(LAS unsigned char* lds, const bf16* QKV, bf16* O, const float* rope, const float* sinks) {
;     ...
;             for (int j = 0; j < 10; ++j) { const LAS bf16* kp = Kl + ((a + j) * 16 + fr) * KP + fq * 8;
;                 f32x4 z = (f32x4){0.f, 0.f, 0.f, 0.f};
;                 z = __builtin_amdgcn_mfma_f32_16x16x32_bf16(*(const LAS bf16x8*)kp, qf[0], z, 0, 0, 0);
;                 z = __builtin_amdgcn_mfma_f32_16x16x32_bf16(*(const LAS bf16x8*)(kp + 32), qf[1], z, 0, 0, 0);
;                 sc[j] = z; }
;             const int qpos = 128 + qi; float mx = -INFINITY;
; #pragma unroll
;             for (int j = 0; j < 10; ++j)
; #pragma unroll
;                 for (int e = 0; e < 4; ++e) { const int kpos = (a + j) * 16 + 4 * fq + e; const bool valid = (kpos <= qpos) && (kpos > qpos - 128) && (nb > 0 || kpos >= 128);
;                     const float sv = valid ? sc[j][e] * 0.125f : -INFINITY; sc[j][e] = sv; mx = fmaxf(mx, sv); }
	v_mfma_f32_16x16x32_bf16 v[88:91], v[222:225], v[76:79], v[80:83]
	s_nop 4
	s_waitcnt lgkmcnt(5)
	v_mfma_f32_16x16x32_bf16 v[84:87], v[226:229], v[92:95], 0
	v_mul_f32_e32 v88, 0x3e000000, v88
	v_mul_f32_e32 v89, 0x3e000000, v89
	v_mul_f32_e32 v90, 0x3e000000, v90
	s_waitcnt lgkmcnt(4)
	v_mfma_f32_16x16x32_bf16 v[84:87], v[230:233], v[76:79], v[84:87]
	v_or_b32_e32 v80, s46, v34
	v_mad_u64_u32 v[146:147], s[18:19], v80, s42, v[106:107]
	s_waitcnt lgkmcnt(3)
	v_mfma_f32_16x16x32_bf16 v[80:83], v[234:237], v[92:95], 0
	v_mul_f32_e32 v91, 0x3e000000, v91
	v_mul_f32_e32 v84, 0x3e000000, v84
	s_waitcnt lgkmcnt(2)
	v_mfma_f32_16x16x32_bf16 v[80:83], v[238:241], v[76:79], v[80:83]
	v_mul_f32_e32 v85, 0x3e000000, v85
	v_mul_f32_e32 v86, 0x3e000000, v86
	s_waitcnt lgkmcnt(1)
	v_mfma_f32_16x16x32_bf16 v[92:95], v[242:245], v[92:95], 0
	v_mul_f32_e32 v87, 0x3e000000, v87
	s_nop 1
	v_mul_f32_e32 v80, 0x3e000000, v80
	v_mul_f32_e32 v82, 0x3e000000, v82
	s_waitcnt lgkmcnt(0)
	v_mfma_f32_16x16x32_bf16 v[76:79], v[246:249], v[76:79], v[92:95]
	s_nop 2
	v_or_b32_e32 v93, s28, v108
	v_mul_f32_e32 v95, 0x3e000000, v97
	v_or_b32_e32 v97, 2, v93
	v_cmp_gt_u32_e32 vcc, v97, v113
	v_mul_f32_e32 v97, 0x3e000000, v98
	s_and_b64 vcc, s[36:37], vcc
	v_or_b32_e32 v93, 3, v93
	v_cndmask_b32_e32 v97, v124, v97, vcc
	v_cmp_gt_u32_e32 vcc, v93, v113
	v_or_b32_e32 v92, 0x80, v113
	v_mul_f32_e32 v93, 0x3e000000, v99
	s_and_b64 vcc, s[36:37], vcc
	v_or_b32_e32 v98, s54, v108
	v_cndmask_b32_e32 v93, v124, v93, vcc
	v_cmp_le_u32_e32 vcc, v98, v92
	v_cmp_gt_u32_e64 s[18:19], v98, v113
	s_and_b64 s[18:19], vcc, s[18:19]
	s_cmp_gt_u32 s50, 6
	s_cselect_b64 s[54:55], -1, 0
	s_or_b64 s[54:55], s[36:37], s[54:55]
	v_mul_f32_e32 v99, 0x3e000000, v126
	s_and_b64 vcc, s[18:19], s[54:55]
	v_cndmask_b32_e32 v99, v124, v99, vcc
	v_cmp_lt_u32_e32 vcc, v98, v92
	v_cmp_ge_u32_e64 s[18:19], v98, v113
	s_and_b64 s[18:19], vcc, s[18:19]
	s_and_b64 vcc, s[18:19], s[54:55]
	v_or_b32_e32 v125, 2, v98
	v_cndmask_b32_e32 v115, v124, v115, vcc
	v_cmp_le_u32_e32 vcc, v125, v92
	v_cmp_gt_u32_e64 s[18:19], v125, v113
	s_and_b64 s[18:19], vcc, s[18:19]
	v_mul_f32_e32 v125, 0x3e000000, v128
	s_and_b64 vcc, s[18:19], s[54:55]
	v_or_b32_e32 v98, 3, v98
	v_cndmask_b32_e32 v125, v124, v125, vcc
	v_cmp_le_u32_e32 vcc, v98, v92
	v_cmp_gt_u32_e64 s[18:19], v98, v113
	s_and_b64 s[18:19], vcc, s[18:19]
	v_mul_f32_e32 v98, 0x3e000000, v129
	s_and_b64 vcc, s[18:19], s[54:55]
	v_or_b32_e32 v126, s49, v108
	v_cndmask_b32_e32 v98, v124, v98, vcc
	v_cmp_le_u32_e32 vcc, v126, v92
	v_cmp_gt_u32_e64 s[18:19], v126, v113
	s_and_b64 s[18:19], vcc, s[18:19]
	s_cmpk_gt_u32 s28, 0x5f
	s_cselect_b64 s[54:55], -1, 0
	s_or_b64 s[54:55], s[36:37], s[54:55]
	s_and_b64 vcc, s[54:55], s[18:19]
	v_cndmask_b32_e32 v127, v124, v127, vcc
	v_cmp_lt_u32_e32 vcc, v126, v92
	v_cmp_ge_u32_e64 s[18:19], v126, v113
	s_and_b64 s[18:19], vcc, s[18:19]
	v_mul_f32_e32 v128, 0x3e000000, v131
	s_and_b64 vcc, s[54:55], s[18:19]
	v_or_b32_e32 v129, 2, v126
	v_cndmask_b32_e32 v128, v124, v128, vcc
	v_cmp_le_u32_e32 vcc, v129, v92
	v_cmp_gt_u32_e64 s[18:19], v129, v113
	s_and_b64 s[18:19], vcc, s[18:19]
	v_mul_f32_e32 v129, 0x3e000000, v132
	s_and_b64 vcc, s[54:55], s[18:19]
	v_or_b32_e32 v126, 3, v126
	v_cndmask_b32_e32 v129, v124, v129, vcc
	v_cmp_le_u32_e32 vcc, v126, v92
	v_cmp_gt_u32_e64 s[18:19], v126, v113
	s_and_b64 s[18:19], vcc, s[18:19]
	v_mul_f32_e32 v126, 0x3e000000, v133
	s_and_b64 vcc, s[54:55], s[18:19]
	v_cndmask_b32_e32 v126, v124, v126, vcc
	v_cmp_le_u32_e32 vcc, v130, v92
	v_cmp_gt_u32_e64 s[18:19], v130, v113
	s_and_b64 s[18:19], vcc, s[18:19]
	s_cmpk_gt_u32 s28, 0x4f
	s_cselect_b64 s[54:55], -1, 0
	s_or_b64 s[54:55], s[36:37], s[54:55]
	v_mul_f32_e32 v131, 0x3e000000, v134
	s_and_b64 vcc, s[54:55], s[18:19]
	v_cndmask_b32_e32 v131, v124, v131, vcc
	v_cmp_lt_u32_e32 vcc, v130, v92
	v_cmp_ge_u32_e64 s[18:19], v130, v113
	s_and_b64 s[18:19], vcc, s[18:19]
	v_mul_f32_e32 v132, 0x3e000000, v135
	s_and_b64 vcc, s[54:55], s[18:19]
	v_or_b32_e32 v133, 2, v130
	v_cndmask_b32_e32 v132, v124, v132, vcc
	v_cmp_le_u32_e32 vcc, v133, v92
	v_cmp_gt_u32_e64 s[18:19], v133, v113
	s_and_b64 s[18:19], vcc, s[18:19]
	v_mul_f32_e32 v133, 0x3e000000, v136
	s_and_b64 vcc, s[54:55], s[18:19]
	v_or_b32_e32 v130, 3, v130
	v_cndmask_b32_e32 v133, v124, v133, vcc
	v_cmp_le_u32_e32 vcc, v130, v92
	v_cmp_gt_u32_e64 s[18:19], v130, v113
	s_and_b64 s[18:19], vcc, s[18:19]
	v_mul_f32_e32 v130, 0x3e000000, v137
	s_and_b64 vcc, s[54:55], s[18:19]
	v_or_b32_e32 v134, s48, v108
	v_cndmask_b32_e32 v130, v124, v130, vcc
	v_cmp_le_u32_e32 vcc, v134, v92
	v_cmp_gt_u32_e64 s[18:19], v134, v113
	s_and_b64 s[18:19], vcc, s[18:19]
	s_cmp_gt_u32 s28, 63
	s_cselect_b64 s[54:55], -1, 0
	s_or_b64 s[54:55], s[36:37], s[54:55]
	v_mul_f32_e32 v135, 0x3e000000, v138
	s_and_b64 vcc, s[54:55], s[18:19]
	v_cndmask_b32_e32 v135, v124, v135, vcc
	v_cmp_lt_u32_e32 vcc, v134, v92
	v_cmp_ge_u32_e64 s[18:19], v134, v113
	s_and_b64 s[18:19], vcc, s[18:19]
	v_mul_f32_e32 v136, 0x3e000000, v139
	s_and_b64 vcc, s[54:55], s[18:19]
	v_or_b32_e32 v137, 2, v134
	v_cndmask_b32_e32 v136, v124, v136, vcc
	v_cmp_le_u32_e32 vcc, v137, v92
	v_cmp_gt_u32_e64 s[18:19], v137, v113
	s_and_b64 s[18:19], vcc, s[18:19]
	v_mul_f32_e32 v137, 0x3e000000, v140
	s_and_b64 vcc, s[54:55], s[18:19]
	v_or_b32_e32 v134, 3, v134
	v_cndmask_b32_e32 v137, v124, v137, vcc
	v_cmp_le_u32_e32 vcc, v134, v92
	v_cmp_gt_u32_e64 s[18:19], v134, v113
	s_and_b64 s[18:19], vcc, s[18:19]
	v_mul_f32_e32 v134, 0x3e000000, v141
	s_and_b64 vcc, s[54:55], s[18:19]
	v_or_b32_e32 v138, s53, v108
	v_cndmask_b32_e32 v134, v124, v134, vcc
; __device__ __forceinline__ void attn_phase(LAS unsigned char* lds, const bf16* QKV, bf16* O, const float* rope, const float* sinks) {
;     ...
;             const int qpos = 128 + qi; float mx = -INFINITY;
; #pragma unroll
;             for (int j = 0; j < 10; ++j)
; #pragma unroll
;                 for (int e = 0; e < 4; ++e) { const int kpos = (a + j) * 16 + 4 * fq + e; const bool valid = (kpos <= qpos) && (kpos > qpos - 128) && (nb > 0 || kpos >= 128);
;                     const float sv = valid ? sc[j][e] * 0.125f : -INFINITY; sc[j][e] = sv; mx = fmaxf(mx, sv); }
;             mx = fmaxf(mx, __shfl_xor(mx, 16)); mx = fmaxf(mx, __shfl_xor(mx, 32)); mx = fmaxf(mx, sink);
	v_cmp_le_u32_e32 vcc, v138, v92
	v_cmp_gt_u32_e64 s[18:19], v138, v113
	s_and_b64 s[18:19], vcc, s[18:19]
	s_cmp_gt_u32 s28, 47
	s_cselect_b64 s[54:55], -1, 0
	s_or_b64 s[54:55], s[36:37], s[54:55]
	v_mul_f32_e32 v139, 0x3e000000, v142
	s_and_b64 vcc, s[54:55], s[18:19]
	v_cndmask_b32_e32 v139, v124, v139, vcc
	v_cmp_lt_u32_e32 vcc, v138, v92
	v_cmp_ge_u32_e64 s[18:19], v138, v113
	s_and_b64 s[18:19], vcc, s[18:19]
	v_mul_f32_e32 v140, 0x3e000000, v143
	s_and_b64 vcc, s[54:55], s[18:19]
	v_or_b32_e32 v141, 2, v138
	v_cndmask_b32_e32 v140, v124, v140, vcc
	v_cmp_le_u32_e32 vcc, v141, v92
	v_cmp_gt_u32_e64 s[18:19], v141, v113
	s_and_b64 s[18:19], vcc, s[18:19]
	v_mul_f32_e32 v141, 0x3e000000, v144
	s_and_b64 vcc, s[54:55], s[18:19]
	v_or_b32_e32 v138, 3, v138
	v_cndmask_b32_e32 v141, v124, v141, vcc
	v_cmp_le_u32_e32 vcc, v138, v92
	v_cmp_gt_u32_e64 s[18:19], v138, v113
	s_and_b64 s[18:19], vcc, s[18:19]
	v_mul_f32_e32 v138, 0x3e000000, v145
	s_and_b64 vcc, s[54:55], s[18:19]
	v_or_b32_e32 v142, s47, v108
	v_cndmask_b32_e32 v138, v124, v138, vcc
	v_cmp_le_u32_e32 vcc, v142, v92
	v_cmp_gt_u32_e64 s[18:19], v142, v113
	s_and_b64 s[18:19], vcc, s[18:19]
	s_cmp_gt_u32 s28, 31
	s_cselect_b64 s[54:55], -1, 0
	s_or_b64 s[54:55], s[36:37], s[54:55]
	s_and_b64 vcc, s[54:55], s[18:19]
	v_cndmask_b32_e32 v88, v124, v88, vcc
	v_cmp_lt_u32_e32 vcc, v142, v92
	v_cmp_ge_u32_e64 s[18:19], v142, v113
	s_and_b64 s[18:19], vcc, s[18:19]
	s_and_b64 vcc, s[54:55], s[18:19]
	v_or_b32_e32 v143, 2, v142
	v_cndmask_b32_e32 v89, v124, v89, vcc
	v_cmp_le_u32_e32 vcc, v143, v92
	v_cmp_gt_u32_e64 s[18:19], v143, v113
	s_and_b64 s[18:19], vcc, s[18:19]
	s_and_b64 vcc, s[54:55], s[18:19]
	v_or_b32_e32 v142, 3, v142
	v_cndmask_b32_e32 v90, v124, v90, vcc
	v_cmp_le_u32_e32 vcc, v142, v92
	v_cmp_gt_u32_e64 s[18:19], v142, v113
	s_and_b64 s[18:19], vcc, s[18:19]
	s_and_b64 vcc, s[54:55], s[18:19]
	v_or_b32_e32 v142, s52, v108
	v_cndmask_b32_e32 v91, v124, v91, vcc
	v_cmp_le_u32_e32 vcc, v142, v92
	v_cmp_gt_u32_e64 s[18:19], v142, v113
	s_and_b64 s[18:19], vcc, s[18:19]
	v_mul_f32_e32 v94, 0x3e000000, v96
	s_cmp_lg_u32 s28, 0
	v_cndmask_b32_e64 v94, v124, v94, s[14:15]
	v_cndmask_b32_e64 v95, v124, v95, s[16:17]
	s_cselect_b64 s[52:53], -1, 0
	v_max3_f32 v96, v94, s43, v95
	s_or_b64 s[52:53], s[36:37], s[52:53]
	v_max3_f32 v96, v96, v97, v93
	s_and_b64 vcc, s[52:53], s[18:19]
	v_max3_f32 v96, v96, v99, v115
	v_cndmask_b32_e32 v84, v124, v84, vcc
	v_cmp_lt_u32_e32 vcc, v142, v92
	v_cmp_ge_u32_e64 s[18:19], v142, v113
	v_max3_f32 v96, v96, v125, v98
	s_and_b64 s[18:19], vcc, s[18:19]
	v_max3_f32 v96, v96, v127, v128
	s_and_b64 vcc, s[52:53], s[18:19]
	v_or_b32_e32 v143, 2, v142
	v_max3_f32 v96, v96, v129, v126
	v_cndmask_b32_e32 v85, v124, v85, vcc
	v_cmp_le_u32_e32 vcc, v143, v92
	v_cmp_gt_u32_e64 s[18:19], v143, v113
	v_max3_f32 v96, v96, v131, v132
	s_and_b64 s[18:19], vcc, s[18:19]
	v_max3_f32 v96, v96, v133, v130
	s_and_b64 vcc, s[52:53], s[18:19]
	v_or_b32_e32 v142, 3, v142
	v_max3_f32 v96, v96, v135, v136
	v_cndmask_b32_e32 v86, v124, v86, vcc
	v_cmp_le_u32_e32 vcc, v142, v92
	v_cmp_gt_u32_e64 s[18:19], v142, v113
	v_max3_f32 v96, v96, v137, v134
	s_and_b64 s[18:19], vcc, s[18:19]
	v_max3_f32 v96, v96, v139, v140
	s_and_b64 vcc, s[52:53], s[18:19]
	v_or_b32_e32 v113, s46, v108
	v_max3_f32 v96, v96, v141, v138
	v_cndmask_b32_e32 v87, v124, v87, vcc
	v_cmp_le_u32_e32 vcc, v113, v92
	v_max3_f32 v96, v96, v88, v89
	v_max3_f32 v96, v96, v90, v91
	v_cndmask_b32_e32 v142, v124, v80, vcc
	v_mul_f32_e32 v80, 0x3e000000, v81
	v_cmp_lt_u32_e32 vcc, v113, v92
	v_or_b32_e32 v81, 2, v113
	v_max3_f32 v96, v96, v84, v85
	v_cndmask_b32_e32 v143, v124, v80, vcc
	v_cmp_le_u32_e32 vcc, v81, v92
	v_or_b32_e32 v81, 3, v113
	v_max3_f32 v96, v96, v86, v87
	v_cndmask_b32_e32 v144, v124, v82, vcc
	v_mul_f32_e32 v82, 0x3e000000, v83
	v_cmp_le_u32_e32 vcc, v81, v92
	v_or_b32_e32 v81, s51, v108
	v_mul_f32_e32 v76, 0x3e000000, v76
	v_cndmask_b32_e32 v113, v124, v82, vcc
	v_cmp_le_u32_e32 vcc, v81, v92
	v_max3_f32 v80, v96, v142, v143
	v_max3_f32 v80, v80, v144, v113
	v_cndmask_b32_e32 v145, v124, v76, vcc
	v_mul_f32_e32 v76, 0x3e000000, v77
	v_cmp_lt_u32_e32 vcc, v81, v92
	v_mul_f32_e32 v78, 0x3e000000, v78
	v_mul_f32_e32 v79, 0x3e000000, v79
	v_cndmask_b32_e32 v77, v124, v76, vcc
	v_max3_f32 v76, v80, v145, v77
	v_or_b32_e32 v80, 2, v81
	v_cmp_le_u32_e32 vcc, v80, v92
	s_cmp_eq_u32 s45, 8
	s_mov_b32 s50, s45
	v_cndmask_b32_e32 v146, v124, v78, vcc
	v_or_b32_e32 v78, 3, v81
	v_cmp_le_u32_e32 vcc, v78, v92
	s_nop 1
	v_cndmask_b32_e32 v147, v124, v79, vcc
	v_max3_f32 v76, v76, v146, v147
	ds_bpermute_b32 v78, v111, v76
	s_waitcnt lgkmcnt(0)
	v_max_f32_e32 v78, v78, v78
	v_max_f32_e32 v76, v76, v78
	ds_bpermute_b32 v78, v120, v76
	s_waitcnt vmcnt(0) lgkmcnt(0)
; #define LAS __attribute__((address_space(3)))
; __device__ __forceinline__ unsigned pk2(float lo, float hi) { return f2bf(lo) | (f2bf(hi) << 16); }
; __device__ __forceinline__ s16x4 tr_read(const LAS bf16* p) { return __builtin_bit_cast(s16x4, __builtin_amdgcn_ds_read_tr16_b64_v4i16((LAS s16x4*)p)); }
; __device__ __forceinline__ void attn_phase(LAS unsigned char* lds, const bf16* QKV, bf16* O, const float* rope, const float* sinks) {
;     ...
;             mx = fmaxf(mx, __shfl_xor(mx, 16)); mx = fmaxf(mx, __shfl_xor(mx, 32)); mx = fmaxf(mx, sink);
;             float l = 0.f;
; #pragma unroll
;             for (int j = 0; j < 10; ++j)
; #pragma unroll
;                 for (int e = 0; e < 4; ++e) { const float p = __expf(sc[j][e] - mx); sc[j][e] = p; l += p; }
;             l += __shfl_xor(l, 16); l += __shfl_xor(l, 32); l += __expf(sink - mx);
;             const float rl = 1.0f / l;
;             f32x4 oacc[4];
; #pragma unroll
;             for (int c = 0; c < 4; ++c) oacc[c] = (f32x4){0.f, 0.f, 0.f, 0.f};
; #pragma unroll
;             for (int j2 = 0; j2 < 5; ++j2) {
;                 u32x4 pwv; pwv.x = pk2(sc[2 * j2][0], sc[2 * j2][1]); pwv.y = pk2(sc[2 * j2][2], sc[2 * j2][3]); pwv.z = pk2(sc[2 * j2 + 1][0], sc[2 * j2 + 1][1]); pwv.w = pk2(sc[2 * j2 + 1][2], sc[2 * j2 + 1][3]);
;                 const bf16x8 pf = __builtin_bit_cast(bf16x8, pwv);
; #pragma unroll
;                 for (int c = 0; c < 4; ++c) { const LAS bf16* vp = Vl + ((a + 2 * j2) * 16 + 4 * fq + q4) * KP + 16 * c + 4 * p4;
;                     const s16x4 lo = tr_read(vp), hi = tr_read(vp + 16 * KP);
;                     const bf16x8 vf = (bf16x8){lo[0], lo[1], lo[2], lo[3], hi[0], hi[1], hi[2], hi[3]};
;                     oacc[c] = __builtin_amdgcn_mfma_f32_16x16x32_bf16(vf, pf, oacc[c], 0, 0, 0); }
	v_max3_f32 v76, v76, v78, v117
	v_sub_f32_e32 v79, v95, v76
	v_sub_f32_e32 v95, v127, v76
	v_mul_f32_e32 v95, 0x3fb8aa3b, v95
	v_sub_f32_e32 v78, v94, v76
	v_sub_f32_e32 v94, v98, v76
	v_exp_f32_e32 v98, v95
	v_sub_f32_e32 v95, v128, v76
	v_mul_f32_e32 v95, 0x3fb8aa3b, v95
	v_sub_f32_e32 v83, v99, v76
	v_exp_f32_e32 v99, v95
	v_sub_f32_e32 v95, v129, v76
	v_mul_f32_e32 v95, 0x3fb8aa3b, v95
	v_sub_f32_e32 v92, v115, v76
	v_exp_f32_e32 v115, v95
	v_sub_f32_e32 v95, v126, v76
	v_mul_f32_e32 v95, 0x3fb8aa3b, v95
	v_mul_f32_e32 v78, 0x3fb8aa3b, v78
	v_sub_f32_e32 v82, v93, v76
	v_sub_f32_e32 v93, v125, v76
	v_exp_f32_e32 v125, v95
	v_sub_f32_e32 v95, v131, v76
	v_exp_f32_e32 v78, v78
	v_mul_f32_e32 v79, 0x3fb8aa3b, v79
	v_sub_f32_e32 v80, v97, v76
	v_mul_f32_e32 v95, 0x3fb8aa3b, v95
	v_exp_f32_e32 v79, v79
	v_mul_f32_e32 v80, 0x3fb8aa3b, v80
	v_exp_f32_e32 v126, v95
	v_sub_f32_e32 v95, v132, v76
	v_exp_f32_e32 v80, v80
	v_mul_f32_e32 v82, 0x3fb8aa3b, v82
	v_mul_f32_e32 v95, 0x3fb8aa3b, v95
	v_exp_f32_e32 v82, v82
	v_mul_f32_e32 v83, 0x3fb8aa3b, v83
	v_exp_f32_e32 v127, v95
	v_sub_f32_e32 v95, v133, v76
	v_add_f32_e32 v81, 0, v78
	v_exp_f32_e32 v83, v83
	v_mul_f32_e32 v92, 0x3fb8aa3b, v92
	v_mul_f32_e32 v95, 0x3fb8aa3b, v95
	v_add_f32_e32 v81, v79, v81
	v_exp_f32_e32 v92, v92
	v_mul_f32_e32 v93, 0x3fb8aa3b, v93
	v_exp_f32_e32 v128, v95
	v_sub_f32_e32 v95, v130, v76
	v_add_f32_e32 v81, v80, v81
	v_exp_f32_e32 v93, v93
	v_mul_f32_e32 v94, 0x3fb8aa3b, v94
	v_mul_f32_e32 v95, 0x3fb8aa3b, v95
	v_add_f32_e32 v81, v82, v81
	v_exp_f32_e32 v94, v94
	v_exp_f32_e32 v129, v95
	v_sub_f32_e32 v95, v135, v76
	v_add_f32_e32 v81, v83, v81
	v_mul_f32_e32 v95, 0x3fb8aa3b, v95
	v_add_f32_e32 v81, v92, v81
	v_exp_f32_e32 v148, v95
	v_sub_f32_e32 v95, v136, v76
	v_add_f32_e32 v81, v93, v81
	v_mul_f32_e32 v95, 0x3fb8aa3b, v95
	v_add_f32_e32 v81, v94, v81
	v_exp_f32_e32 v149, v95
	v_sub_f32_e32 v95, v137, v76
	v_add_f32_e32 v81, v98, v81
	v_mul_f32_e32 v95, 0x3fb8aa3b, v95
	v_add_f32_e32 v81, v99, v81
	v_exp_f32_e32 v150, v95
	v_sub_f32_e32 v95, v134, v76
	v_add_f32_e32 v81, v115, v81
	v_mul_f32_e32 v95, 0x3fb8aa3b, v95
	v_add_f32_e32 v81, v125, v81
	v_exp_f32_e32 v151, v95
	v_sub_f32_e32 v95, v139, v76
	v_add_f32_e32 v81, v126, v81
	v_mul_f32_e32 v95, 0x3fb8aa3b, v95
	v_add_f32_e32 v81, v127, v81
	v_exp_f32_e32 v152, v95
	v_sub_f32_e32 v95, v140, v76
	v_add_f32_e32 v81, v128, v81
	v_mul_f32_e32 v95, 0x3fb8aa3b, v95
	v_add_f32_e32 v81, v129, v81
	v_exp_f32_e32 v153, v95
	v_sub_f32_e32 v95, v141, v76
	v_sub_f32_e32 v88, v88, v76
	v_add_f32_e32 v81, v148, v81
	v_mul_f32_e32 v95, 0x3fb8aa3b, v95
	v_mul_f32_e32 v88, 0x3fb8aa3b, v88
	v_add_f32_e32 v81, v149, v81
	v_exp_f32_e32 v154, v95
	v_sub_f32_e32 v95, v138, v76
	v_exp_f32_e32 v156, v88
	v_sub_f32_e32 v88, v89, v76
	v_add_f32_e32 v81, v150, v81
	v_mul_f32_e32 v95, 0x3fb8aa3b, v95
	v_mul_f32_e32 v88, 0x3fb8aa3b, v88
	v_add_f32_e32 v81, v151, v81
	v_exp_f32_e32 v155, v95
	v_exp_f32_e32 v157, v88
	v_sub_f32_e32 v88, v90, v76
	v_add_f32_e32 v81, v152, v81
	v_mul_f32_e32 v88, 0x3fb8aa3b, v88
	v_sub_f32_e32 v84, v84, v76
	v_add_f32_e32 v81, v153, v81
	v_exp_f32_e32 v158, v88
	v_sub_f32_e32 v88, v91, v76
	v_mul_f32_e32 v84, 0x3fb8aa3b, v84
	v_add_f32_e32 v81, v154, v81
	v_mul_f32_e32 v88, 0x3fb8aa3b, v88
	v_exp_f32_e32 v160, v84
	v_sub_f32_e32 v84, v85, v76
	v_add_f32_e32 v81, v155, v81
	v_exp_f32_e32 v159, v88
	v_mul_f32_e32 v84, 0x3fb8aa3b, v84
	v_add_f32_e32 v81, v156, v81
	v_exp_f32_e32 v161, v84
	v_sub_f32_e32 v84, v86, v76
	v_add_f32_e32 v81, v157, v81
	v_mul_f32_e32 v84, 0x3fb8aa3b, v84
	v_add_f32_e32 v81, v158, v81
	v_exp_f32_e32 v162, v84
	v_add_f32_e32 v81, v159, v81
	v_add_f32_e32 v81, v160, v81
	v_add_f32_e32 v81, v161, v81
	v_bfe_u32 v85, v82, 16, 1
	v_bfe_u32 v86, v79, 16, 1
	v_add_f32_e32 v130, v162, v81
	v_sub_f32_e32 v81, v87, v76
	v_add3_u32 v86, v79, v86, s39
	v_add3_u32 v79, v82, v85, s39
	v_bfe_u32 v85, v80, 16, 1
	v_bfe_u32 v87, v83, 16, 1
	v_bfe_u32 v84, v92, 16, 1
	v_add3_u32 v83, v83, v87, s39
	v_add3_u32 v80, v80, v85, s39
	v_mul_f32_e32 v81, 0x3fb8aa3b, v81
	v_add3_u32 v82, v92, v84, s39
	v_bfe_u32 v84, v78, 16, 1
	v_bfe_u32 v88, v93, 16, 1
	v_lshrrev_b32_e32 v87, 16, v80
	v_lshrrev_b32_e32 v80, 16, v83
	v_exp_f32_e32 v163, v81
	v_bfe_u32 v81, v94, 16, 1
	v_add3_u32 v88, v93, v88, s39
	v_add3_u32 v78, v78, v84, s39
	v_and_or_b32 v80, v82, s38, v80
	v_or_b32_e32 v82, s28, v121
	v_sub_f32_e32 v131, v142, v76
	v_add3_u32 v81, v94, v81, s39
	v_lshrrev_b32_e32 v78, 16, v78
	v_lshrrev_b32_e32 v83, 16, v88
	v_mad_u64_u32 v[96:97], s[18:19], v82, s42, v[110:111]
	v_mul_f32_e32 v131, 0x3fb8aa3b, v131
	v_and_or_b32 v81, v81, s38, v83
	ds_read_b64_tr_b16 v[84:85], v96 offset:41472
	ds_read_b64_tr_b16 v[82:83], v96 offset:39168
	v_and_or_b32 v79, v79, s38, v87
	v_and_or_b32 v78, v86, s38, v78
	ds_read_b64_tr_b16 v[88:89], v96 offset:41504
	ds_read_b64_tr_b16 v[86:87], v96 offset:39200
	ds_read_b64_tr_b16 v[90:91], v96 offset:39232
	ds_read_b64_tr_b16 v[94:95], v96 offset:39264
	ds_read_b64_tr_b16 v[92:93], v96 offset:41536
	ds_read_b64_tr_b16 v[96:97], v96 offset:41568
	v_exp_f32_e32 v142, v131
	v_sub_f32_e32 v131, v143, v76
	v_mul_f32_e32 v131, 0x3fb8aa3b, v131
	v_exp_f32_e32 v143, v131
	v_add_f32_e32 v130, v163, v130
	s_waitcnt lgkmcnt(6)
	v_mfma_f32_16x16x32_bf16 v[82:85], v[82:85], v[78:81], 0
	v_add_f32_e32 v130, v142, v130
	v_add_f32_e32 v164, v143, v130
	v_sub_f32_e32 v77, v77, v76
	s_waitcnt lgkmcnt(4)
	v_mfma_f32_16x16x32_bf16 v[86:89], v[86:89], v[78:81], 0
	v_mul_f32_e32 v77, 0x3fb8aa3b, v77
	v_exp_f32_e32 v77, v77
	s_waitcnt lgkmcnt(1)
	v_mfma_f32_16x16x32_bf16 v[90:93], v[90:93], v[78:81], 0
	s_waitcnt lgkmcnt(0)
; #define LAS __attribute__((address_space(3)))
; __device__ __forceinline__ unsigned pk2(float lo, float hi) { return f2bf(lo) | (f2bf(hi) << 16); }
; __device__ __forceinline__ s16x4 tr_read(const LAS bf16* p) { return __builtin_bit_cast(s16x4, __builtin_amdgcn_ds_read_tr16_b64_v4i16((LAS s16x4*)p)); }
; __device__ __forceinline__ void attn_phase(LAS unsigned char* lds, const bf16* QKV, bf16* O, const float* rope, const float* sinks) {
;     ...
;             for (int j2 = 0; j2 < 5; ++j2) {
;                 u32x4 pwv; pwv.x = pk2(sc[2 * j2][0], sc[2 * j2][1]); pwv.y = pk2(sc[2 * j2][2], sc[2 * j2][3]); pwv.z = pk2(sc[2 * j2 + 1][0], sc[2 * j2 + 1][1]); pwv.w = pk2(sc[2 * j2 + 1][2], sc[2 * j2 + 1][3]);
;                 const bf16x8 pf = __builtin_bit_cast(bf16x8, pwv);
; #pragma unroll
;                 for (int c = 0; c < 4; ++c) { const LAS bf16* vp = Vl + ((a + 2 * j2) * 16 + 4 * fq + q4) * KP + 16 * c + 4 * p4;
;                     const s16x4 lo = tr_read(vp), hi = tr_read(vp + 16 * KP);
;                     const bf16x8 vf = (bf16x8){lo[0], lo[1], lo[2], lo[3], hi[0], hi[1], hi[2], hi[3]};
;                     oacc[c] = __builtin_amdgcn_mfma_f32_16x16x32_bf16(vf, pf, oacc[c], 0, 0, 0); }
	v_mfma_f32_16x16x32_bf16 v[78:81], v[94:97], v[78:81], 0
	v_bfe_u32 v95, v127, 16, 1
	v_bfe_u32 v97, v99, 16, 1
	v_add3_u32 v130, v99, v97, s39
	v_add3_u32 v95, v127, v95, s39
	v_bfe_u32 v97, v115, 16, 1
	v_bfe_u32 v127, v128, 16, 1
	v_bfe_u32 v94, v129, 16, 1
	v_bfe_u32 v96, v125, 16, 1
	v_add3_u32 v127, v128, v127, s39
	v_add3_u32 v97, v115, v97, s39
	v_add3_u32 v125, v125, v96, s39
	v_add3_u32 v94, v129, v94, s39
	v_bfe_u32 v96, v98, 16, 1
	v_bfe_u32 v99, v126, 16, 1
	v_lshrrev_b32_e32 v131, 16, v97
	v_lshrrev_b32_e32 v97, 16, v127
	v_add3_u32 v99, v126, v99, s39
	v_add3_u32 v96, v98, v96, s39
	v_and_or_b32 v97, v94, s38, v97
	v_or_b32_e32 v94, s49, v121
	v_lshrrev_b32_e32 v115, 16, v96
	v_lshrrev_b32_e32 v96, 16, v99
	v_mad_u64_u32 v[98:99], s[18:19], v94, s42, v[110:111]
	v_and_or_b32 v96, v95, s38, v96
	ds_read_b64_tr_b16 v[128:129], v98 offset:41472
	ds_read_b64_tr_b16 v[126:127], v98 offset:39168
	v_and_or_b32 v95, v125, s38, v131
	v_and_or_b32 v94, v130, s38, v115
	ds_read_b64_tr_b16 v[132:133], v98 offset:41504
	ds_read_b64_tr_b16 v[130:131], v98 offset:39200
	ds_read_b64_tr_b16 v[134:135], v98 offset:39232
	ds_read_b64_tr_b16 v[138:139], v98 offset:39264
	ds_read_b64_tr_b16 v[136:137], v98 offset:41536
	ds_read_b64_tr_b16 v[140:141], v98 offset:41568
	v_sub_f32_e32 v98, v144, v76
	v_mul_f32_e32 v98, 0x3fb8aa3b, v98
	v_exp_f32_e32 v115, v98
	v_sub_f32_e32 v98, v113, v76
	s_waitcnt lgkmcnt(6)
	v_mfma_f32_16x16x32_bf16 v[82:85], v[126:129], v[94:97], v[82:85]
	v_mul_f32_e32 v98, 0x3fb8aa3b, v98
	v_exp_f32_e32 v113, v98
	v_sub_f32_e32 v98, v145, v76
	s_waitcnt lgkmcnt(4)
	v_mfma_f32_16x16x32_bf16 v[86:89], v[130:133], v[94:97], v[86:89]
	v_bfe_u32 v99, v154, 16, 1
	v_mul_f32_e32 v98, 0x3fb8aa3b, v98
	v_add3_u32 v99, v154, v99, s39
	s_waitcnt lgkmcnt(1)
	v_mfma_f32_16x16x32_bf16 v[90:93], v[134:137], v[94:97], v[90:93]
	v_exp_f32_e32 v125, v98
	v_bfe_u32 v98, v152, 16, 1
	v_add3_u32 v98, v152, v98, s39
	s_waitcnt lgkmcnt(0)
	v_mfma_f32_16x16x32_bf16 v[78:81], v[138:141], v[94:97], v[78:81]
	v_bfe_u32 v97, v149, 16, 1
	v_add3_u32 v130, v149, v97, s39
	v_bfe_u32 v97, v150, 16, 1
	v_bfe_u32 v94, v155, 16, 1
	v_bfe_u32 v96, v151, 16, 1
	v_add3_u32 v97, v150, v97, s39
	v_add3_u32 v131, v151, v96, s39
	v_add3_u32 v94, v155, v94, s39
	v_bfe_u32 v96, v148, 16, 1
	v_lshrrev_b32_e32 v133, 16, v97
	v_lshrrev_b32_e32 v97, 16, v99
	v_bfe_u32 v95, v153, 16, 1
	v_add3_u32 v96, v148, v96, s39
	v_and_or_b32 v97, v94, s38, v97
	v_or_b32_e32 v94, s48, v121
	v_add3_u32 v95, v153, v95, s39
	v_lshrrev_b32_e32 v132, 16, v96
	v_lshrrev_b32_e32 v96, 16, v98
	v_mad_u64_u32 v[98:99], s[18:19], v94, s42, v[110:111]
	v_and_or_b32 v96, v95, s38, v96
	ds_read_b64_tr_b16 v[128:129], v98 offset:41472
	ds_read_b64_tr_b16 v[126:127], v98 offset:39168
	v_and_or_b32 v95, v131, s38, v133
	v_and_or_b32 v94, v130, s38, v132
	ds_read_b64_tr_b16 v[132:133], v98 offset:41504
	ds_read_b64_tr_b16 v[130:131], v98 offset:39200
	ds_read_b64_tr_b16 v[134:135], v98 offset:39232
	ds_read_b64_tr_b16 v[138:139], v98 offset:39264
	ds_read_b64_tr_b16 v[136:137], v98 offset:41536
	ds_read_b64_tr_b16 v[140:141], v98 offset:41568
	v_add_f32_e32 v98, v115, v164
	s_waitcnt lgkmcnt(6)
	v_mfma_f32_16x16x32_bf16 v[82:85], v[126:129], v[94:97], v[82:85]
	v_add_f32_e32 v98, v113, v98
	v_add_f32_e32 v144, v125, v98
	v_sub_f32_e32 v98, v146, v76
	s_waitcnt lgkmcnt(4)
	v_mfma_f32_16x16x32_bf16 v[86:89], v[130:133], v[94:97], v[86:89]
	v_bfe_u32 v99, v162, 16, 1
	v_mul_f32_e32 v98, 0x3fb8aa3b, v98
	v_add3_u32 v99, v162, v99, s39
	s_waitcnt lgkmcnt(1)
	v_mfma_f32_16x16x32_bf16 v[90:93], v[134:137], v[94:97], v[90:93]
	v_exp_f32_e32 v145, v98
	v_bfe_u32 v98, v160, 16, 1
	v_add3_u32 v98, v160, v98, s39
	s_waitcnt lgkmcnt(0)
	v_mfma_f32_16x16x32_bf16 v[78:81], v[138:141], v[94:97], v[78:81]
	v_bfe_u32 v97, v157, 16, 1
	v_add3_u32 v130, v157, v97, s39
	v_bfe_u32 v97, v158, 16, 1
	v_bfe_u32 v94, v163, 16, 1
	v_bfe_u32 v96, v159, 16, 1
	v_add3_u32 v97, v158, v97, s39
	v_add3_u32 v131, v159, v96, s39
	v_add3_u32 v94, v163, v94, s39
	v_bfe_u32 v96, v156, 16, 1
	v_lshrrev_b32_e32 v133, 16, v97
	v_lshrrev_b32_e32 v97, 16, v99
	v_bfe_u32 v95, v161, 16, 1
	v_add3_u32 v96, v156, v96, s39
	v_and_or_b32 v97, v94, s38, v97
	v_or_b32_e32 v94, s47, v121
	v_add3_u32 v95, v161, v95, s39
	v_lshrrev_b32_e32 v132, 16, v96
	v_lshrrev_b32_e32 v96, 16, v98
	v_mad_u64_u32 v[98:99], s[18:19], v94, s42, v[110:111]
	v_and_or_b32 v96, v95, s38, v96
	ds_read_b64_tr_b16 v[128:129], v98 offset:41472
	ds_read_b64_tr_b16 v[126:127], v98 offset:39168
	v_and_or_b32 v95, v131, s38, v133
	v_and_or_b32 v94, v130, s38, v132
	ds_read_b64_tr_b16 v[132:133], v98 offset:41504
	ds_read_b64_tr_b16 v[130:131], v98 offset:39200
	ds_read_b64_tr_b16 v[134:135], v98 offset:39232
	ds_read_b64_tr_b16 v[138:139], v98 offset:39264
	ds_read_b64_tr_b16 v[136:137], v98 offset:41536
	ds_read_b64_tr_b16 v[140:141], v98 offset:41568
	v_sub_f32_e32 v98, v147, v76
	v_mul_f32_e32 v98, 0x3fb8aa3b, v98
	v_exp_f32_e32 v98, v98
	v_add_f32_e32 v99, v77, v144
	v_add_f32_e32 v99, v145, v99
	s_waitcnt lgkmcnt(6)
	v_mfma_f32_16x16x32_bf16 v[82:85], v[126:129], v[94:97], v[82:85]
	v_add_f32_e32 v99, v98, v99
	ds_bpermute_b32 v126, v111, v99
	v_sub_f32_e32 v76, v117, v76
	s_waitcnt lgkmcnt(5)
	v_mfma_f32_16x16x32_bf16 v[86:89], v[130:133], v[94:97], v[86:89]
	v_mul_f32_e32 v76, 0x3fb8aa3b, v76
	v_exp_f32_e32 v76, v76
	s_waitcnt lgkmcnt(0)
; #define LAS __attribute__((address_space(3)))
; __device__ __forceinline__ unsigned pk2(float lo, float hi) { return f2bf(lo) | (f2bf(hi) << 16); }
; __device__ __forceinline__ s16x4 tr_read(const LAS bf16* p) { return __builtin_bit_cast(s16x4, __builtin_amdgcn_ds_read_tr16_b64_v4i16((LAS s16x4*)p)); }
; __device__ __forceinline__ void attn_phase(LAS unsigned char* lds, const bf16* QKV, bf16* O, const float* rope, const float* sinks) {
;     ...
;             l += __shfl_xor(l, 16); l += __shfl_xor(l, 32); l += __expf(sink - mx);
;             const float rl = 1.0f / l;
;             f32x4 oacc[4];
; #pragma unroll
;             for (int c = 0; c < 4; ++c) oacc[c] = (f32x4){0.f, 0.f, 0.f, 0.f};
; #pragma unroll
;             for (int j2 = 0; j2 < 5; ++j2) {
;                 u32x4 pwv; pwv.x = pk2(sc[2 * j2][0], sc[2 * j2][1]); pwv.y = pk2(sc[2 * j2][2], sc[2 * j2][3]); pwv.z = pk2(sc[2 * j2 + 1][0], sc[2 * j2 + 1][1]); pwv.w = pk2(sc[2 * j2 + 1][2], sc[2 * j2 + 1][3]);
;                 const bf16x8 pf = __builtin_bit_cast(bf16x8, pwv);
; #pragma unroll
;                 for (int c = 0; c < 4; ++c) { const LAS bf16* vp = Vl + ((a + 2 * j2) * 16 + 4 * fq + q4) * KP + 16 * c + 4 * p4;
;                     const s16x4 lo = tr_read(vp), hi = tr_read(vp + 16 * KP);
;                     const bf16x8 vf = (bf16x8){lo[0], lo[1], lo[2], lo[3], hi[0], hi[1], hi[2], hi[3]};
;                     oacc[c] = __builtin_amdgcn_mfma_f32_16x16x32_bf16(vf, pf, oacc[c], 0, 0, 0); }
;             }
;             bf16* op = O + qrow * D + (qrow >> 8) * adjo + qh * 64 + 4 * fq;
; #pragma unroll
;             for (int c = 0; c < 4; ++c) { u32x2 w; w.x = pk2(oacc[c][0] * rl, oacc[c][1] * rl); w.y = pk2(oacc[c][2] * rl, oacc[c][3] * rl); *(u32x2*)(op + 16 * c) = w; }
	v_add_f32_e32 v144, v99, v126
	v_mfma_f32_16x16x32_bf16 v[90:93], v[134:137], v[94:97], v[90:93]
	v_mfma_f32_16x16x32_bf16 v[78:81], v[138:141], v[94:97], v[78:81]
	v_bfe_u32 v95, v77, 16, 1
	v_bfe_u32 v96, v113, 16, 1
	v_bfe_u32 v97, v143, 16, 1
	v_add3_u32 v130, v143, v97, s39
	v_add3_u32 v113, v113, v96, s39
	v_add3_u32 v77, v77, v95, s39
	v_bfe_u32 v95, v142, 16, 1
	v_bfe_u32 v96, v115, 16, 1
	v_bfe_u32 v97, v125, 16, 1
	v_bfe_u32 v94, v98, 16, 1
	v_add3_u32 v97, v125, v97, s39
	v_add3_u32 v96, v115, v96, s39
	v_add3_u32 v95, v142, v95, s39
	v_add3_u32 v94, v98, v94, s39
	v_bfe_u32 v98, v145, 16, 1
	v_lshrrev_b32_e32 v115, 16, v95
	v_lshrrev_b32_e32 v95, 16, v96
	v_lshrrev_b32_e32 v96, 16, v97
	v_add3_u32 v98, v145, v98, s39
	v_and_or_b32 v96, v77, s38, v96
	v_or_b32_e32 v77, s46, v121
	v_lshrrev_b32_e32 v97, 16, v98
	v_mad_u64_u32 v[98:99], s[18:19], v77, s42, v[110:111]
	ds_bpermute_b32 v77, v120, v144
	v_and_or_b32 v95, v113, s38, v95
	v_and_or_b32 v97, v94, s38, v97
	ds_read_b64_tr_b16 v[128:129], v98 offset:41472
	ds_read_b64_tr_b16 v[126:127], v98 offset:39168
	v_and_or_b32 v94, v130, s38, v115
	s_waitcnt lgkmcnt(2)
	v_add_f32_e32 v77, v144, v77
	v_add_f32_e32 v113, v76, v77
	ds_read_b64_tr_b16 v[132:133], v98 offset:41504
	ds_read_b64_tr_b16 v[130:131], v98 offset:39200
	ds_read_b64_tr_b16 v[134:135], v98 offset:39232
	ds_read_b64_tr_b16 v[138:139], v98 offset:39264
	ds_read_b64_tr_b16 v[136:137], v98 offset:41536
	ds_read_b64_tr_b16 v[140:141], v98 offset:41568
	v_div_scale_f32 v115, s[18:19], v113, v113, 1.0
	v_rcp_f32_e32 v125, v115
	s_waitcnt lgkmcnt(0)
	v_mfma_f32_16x16x32_bf16 v[76:79], v[138:141], v[94:97], v[78:81]
	v_lshl_add_u64 v[98:99], v[44:45], 0, s[28:29]
	s_nop 1
	v_fma_f32 v80, -v115, v125, 1.0
	v_fmac_f32_e32 v125, v80, v125
	v_div_scale_f32 v80, vcc, 1.0, v113, 1.0
	v_mul_f32_e32 v81, v80, v125
	v_mfma_f32_16x16x32_bf16 v[82:85], v[126:129], v[94:97], v[82:85]
	v_mfma_f32_16x16x32_bf16 v[86:89], v[130:133], v[94:97], v[86:89]
	v_mfma_f32_16x16x32_bf16 v[90:93], v[134:137], v[94:97], v[90:93]
	v_fma_f32 v94, -v115, v81, v80
	v_fmac_f32_e32 v81, v94, v125
	v_fma_f32 v80, -v115, v81, v80
	v_div_fmas_f32 v80, v80, v125, v81
	v_div_fixup_f32 v80, v80, v113, 1.0
	s_nop 0
	v_mov_b32_e32 v96, v82
	v_mov_b32_e32 v97, v84
	v_pk_mul_f32 v[96:97], v[96:97], v[80:81] op_sel_hi:[1,0]
	v_mov_b32_e32 v84, v83
	v_pk_mul_f32 v[82:83], v[84:85], v[80:81] op_sel_hi:[1,0]
	v_and_b32_sdwa v84, v96, v122 dst_sel:DWORD dst_unused:UNUSED_PAD src0_sel:WORD_1 src1_sel:DWORD
	v_add3_u32 v84, v96, v84, s39
	v_and_b32_sdwa v85, v83, v122 dst_sel:DWORD dst_unused:UNUSED_PAD src0_sel:WORD_1 src1_sel:DWORD
	v_and_b32_sdwa v96, v82, v122 dst_sel:DWORD dst_unused:UNUSED_PAD src0_sel:WORD_1 src1_sel:DWORD
	v_and_b32_sdwa v81, v97, v122 dst_sel:DWORD dst_unused:UNUSED_PAD src0_sel:WORD_1 src1_sel:DWORD
	v_add3_u32 v83, v83, v85, s39
	v_add3_u32 v82, v82, v96, s39
	v_lshlrev_b64 v[94:95], 12, v[98:99]
	v_add3_u32 v81, v97, v81, s39
	v_and_b32_e32 v83, 0xffff0000, v83
	v_and_b32_e32 v82, 0xffff0000, v82
	v_lshl_add_u64 v[94:95], v[118:119], 0, v[94:95]
	v_or_b32_sdwa v83, v83, v81 dst_sel:DWORD dst_unused:UNUSED_PAD src0_sel:DWORD src1_sel:WORD_1
	v_or_b32_sdwa v82, v82, v84 dst_sel:DWORD dst_unused:UNUSED_PAD src0_sel:DWORD src1_sel:WORD_1
	global_store_dwordx2 v[94:95], v[82:83], off
	v_mov_b32_e32 v82, v86
	v_mov_b32_e32 v83, v88
	v_pk_mul_f32 v[82:83], v[80:81], v[82:83] op_sel_hi:[0,1]
	v_mov_b32_e32 v88, v87
	v_pk_mul_f32 v[84:85], v[80:81], v[88:89] op_sel_hi:[0,1]
	v_and_b32_sdwa v81, v83, v122 dst_sel:DWORD dst_unused:UNUSED_PAD src0_sel:WORD_1 src1_sel:DWORD
	v_and_b32_sdwa v86, v82, v122 dst_sel:DWORD dst_unused:UNUSED_PAD src0_sel:WORD_1 src1_sel:DWORD
	v_add3_u32 v82, v82, v86, s39
	v_add3_u32 v81, v83, v81, s39
	v_and_b32_sdwa v83, v85, v122 dst_sel:DWORD dst_unused:UNUSED_PAD src0_sel:WORD_1 src1_sel:DWORD
	v_and_b32_sdwa v86, v84, v122 dst_sel:DWORD dst_unused:UNUSED_PAD src0_sel:WORD_1 src1_sel:DWORD
	v_add3_u32 v83, v85, v83, s39
	v_add3_u32 v84, v84, v86, s39
	v_and_b32_e32 v83, 0xffff0000, v83
	v_and_b32_e32 v84, 0xffff0000, v84
	v_or_b32_sdwa v83, v83, v81 dst_sel:DWORD dst_unused:UNUSED_PAD src0_sel:DWORD src1_sel:WORD_1
	v_or_b32_sdwa v82, v84, v82 dst_sel:DWORD dst_unused:UNUSED_PAD src0_sel:DWORD src1_sel:WORD_1
	global_store_dwordx2 v[94:95], v[82:83], off offset:32
	v_mov_b32_e32 v82, v90
	v_mov_b32_e32 v83, v92
	v_pk_mul_f32 v[82:83], v[80:81], v[82:83] op_sel_hi:[0,1]
	v_mov_b32_e32 v92, v91
	v_pk_mul_f32 v[84:85], v[80:81], v[92:93] op_sel_hi:[0,1]
	v_and_b32_sdwa v81, v83, v122 dst_sel:DWORD dst_unused:UNUSED_PAD src0_sel:WORD_1 src1_sel:DWORD
	v_and_b32_sdwa v86, v82, v122 dst_sel:DWORD dst_unused:UNUSED_PAD src0_sel:WORD_1 src1_sel:DWORD
	v_add3_u32 v82, v82, v86, s39
	v_add3_u32 v81, v83, v81, s39
	v_and_b32_sdwa v83, v85, v122 dst_sel:DWORD dst_unused:UNUSED_PAD src0_sel:WORD_1 src1_sel:DWORD
	v_and_b32_sdwa v86, v84, v122 dst_sel:DWORD dst_unused:UNUSED_PAD src0_sel:WORD_1 src1_sel:DWORD
	v_add3_u32 v83, v85, v83, s39
	v_add3_u32 v84, v84, v86, s39
	v_and_b32_e32 v83, 0xffff0000, v83
	v_and_b32_e32 v84, 0xffff0000, v84
	v_or_b32_sdwa v83, v83, v81 dst_sel:DWORD dst_unused:UNUSED_PAD src0_sel:DWORD src1_sel:WORD_1
	v_or_b32_sdwa v82, v84, v82 dst_sel:DWORD dst_unused:UNUSED_PAD src0_sel:DWORD src1_sel:WORD_1
	global_store_dwordx2 v[94:95], v[82:83], off offset:64
	v_mov_b32_e32 v83, v78
	v_mov_b32_e32 v78, v77
	v_mov_b32_e32 v82, v76
	v_pk_mul_f32 v[76:77], v[80:81], v[78:79] op_sel_hi:[0,1]
	v_pk_mul_f32 v[82:83], v[80:81], v[82:83] op_sel_hi:[0,1]
	v_and_b32_sdwa v80, v77, v122 dst_sel:DWORD dst_unused:UNUSED_PAD src0_sel:WORD_1 src1_sel:DWORD
	v_and_b32_sdwa v81, v76, v122 dst_sel:DWORD dst_unused:UNUSED_PAD src0_sel:WORD_1 src1_sel:DWORD
	v_and_b32_sdwa v78, v83, v122 dst_sel:DWORD dst_unused:UNUSED_PAD src0_sel:WORD_1 src1_sel:DWORD
	v_and_b32_sdwa v79, v82, v122 dst_sel:DWORD dst_unused:UNUSED_PAD src0_sel:WORD_1 src1_sel:DWORD
	v_add3_u32 v77, v77, v80, s39
	v_add3_u32 v76, v76, v81, s39
	v_add3_u32 v79, v82, v79, s39
	v_add3_u32 v78, v83, v78, s39
	v_and_b32_e32 v77, 0xffff0000, v77
	v_and_b32_e32 v76, 0xffff0000, v76
	v_or_b32_sdwa v77, v77, v78 dst_sel:DWORD dst_unused:UNUSED_PAD src0_sel:DWORD src1_sel:WORD_1
	v_or_b32_sdwa v76, v76, v79 dst_sel:DWORD dst_unused:UNUSED_PAD src0_sel:DWORD src1_sel:WORD_1
	global_store_dwordx2 v[94:95], v[76:77], off offset:96
	v_mov_b64_e32 v[98:99], v[62:63]
	v_mov_b64_e32 v[94:95], v[66:67]
	v_mov_b64_e32 v[90:91], v[70:71]
	v_mov_b64_e32 v[86:87], v[74:75]
	v_mov_b64_e32 v[82:83], v[58:59]
	v_mov_b64_e32 v[78:79], v[54:55]
	v_mov_b64_e32 v[96:97], v[60:61]
	v_mov_b64_e32 v[92:93], v[64:65]
	v_mov_b64_e32 v[88:89], v[68:69]
	v_mov_b64_e32 v[84:85], v[72:73]
	v_mov_b64_e32 v[80:81], v[56:57]
	v_mov_b64_e32 v[76:77], v[52:53]
	s_cbranch_scc1 .LBB0_1740

; #define LAS __attribute__((address_space(3)))
; __device__ __forceinline__ void attn_phase(LAS unsigned char* lds, const bf16* QKV, bf16* O, const float* rope, const float* sinks) {
	.amdhsa_kernel _Z8mega_fwd4Args
		.amdhsa_group_segment_fixed_size 0
		.amdhsa_private_segment_fixed_size 0
		.amdhsa_kernarg_size 552
		.amdhsa_user_sgpr_count 2
		.amdhsa_user_sgpr_dispatch_ptr 0
		.amdhsa_user_sgpr_queue_ptr 0
		.amdhsa_user_sgpr_kernarg_segment_ptr 1
		.amdhsa_user_sgpr_dispatch_id 0
		.amdhsa_user_sgpr_kernarg_preload_length 0
		.amdhsa_user_sgpr_kernarg_preload_offset 0
		.amdhsa_user_sgpr_private_segment_size 0
		.amdhsa_uses_dynamic_stack 0
		.amdhsa_enable_private_segment 0
		.amdhsa_system_sgpr_workgroup_id_x 1
		.amdhsa_system_sgpr_workgroup_id_y 0
		.amdhsa_system_sgpr_workgroup_id_z 0
		.amdhsa_system_sgpr_workgroup_info 0
		.amdhsa_system_vgpr_workitem_id 2
		.amdhsa_next_free_vgpr 255
		.amdhsa_next_free_sgpr 102
		.amdhsa_accum_offset 256
		.amdhsa_reserve_vcc 1
		.amdhsa_float_round_mode_32 0
		.amdhsa_float_round_mode_16_64 0
		.amdhsa_float_denorm_mode_32 3
		.amdhsa_float_denorm_mode_16_64 3
		.amdhsa_dx10_clamp 1
		.amdhsa_ieee_mode 1
		.amdhsa_fp16_overflow 0
		.amdhsa_tg_split 0
		.amdhsa_exception_fp_ieee_invalid_op 0
		.amdhsa_exception_fp_denorm_src 0
		.amdhsa_exception_fp_ieee_div_zero 0
		.amdhsa_exception_fp_ieee_overflow 0
		.amdhsa_exception_fp_ieee_underflow 0
		.amdhsa_exception_fp_ieee_inexact 0
		.amdhsa_exception_int_div_zero 0
	.end_amdhsa_kernel

; #define LAS __attribute__((address_space(3)))
; __device__ __forceinline__ void attn_phase(LAS unsigned char* lds, const bf16* QKV, bf16* O, const float* rope, const float* sinks) {
.Lfunc_end0:
	.size	_Z8mega_fwd4Args, .Lfunc_end0-_Z8mega_fwd4Args
	.set _Z8mega_fwd4Args.num_vgpr, 255
	.set _Z8mega_fwd4Args.num_agpr, 0
	.set _Z8mega_fwd4Args.numbered_sgpr, 102
	.set _Z8mega_fwd4Args.num_named_barrier, 0
	.set _Z8mega_fwd4Args.private_seg_size, 0
	.set _Z8mega_fwd4Args.uses_vcc, 1
	.set _Z8mega_fwd4Args.uses_flat_scratch, 0
	.set _Z8mega_fwd4Args.has_dyn_sized_stack, 0
	.set _Z8mega_fwd4Args.has_recursion, 0
	.set _Z8mega_fwd4Args.has_indirect_call, 0

; #define LAS __attribute__((address_space(3)))
; __global__ void __launch_bounds__(512, 2) mega_fwd(Args a) {
;     extern __shared__ __attribute__((aligned(16))) unsigned char lds_raw[];
;     LAS unsigned char* lds = (LAS unsigned char*)lds_raw;
;     const int lo = a.lo, hi = a.hi;
;     unsigned* barw = (unsigned*)(a.ws + WS_CTL);
;     volatile LAS unsigned* MISC = (volatile LAS unsigned*)(lds + MISC_OFF);
;     if (threadIdx.x < 16) MISC[threadIdx.x] = 0u;
amdhsa.kernels:
  - .agpr_count:     0
    .args:
      - .offset:         0
        .size:           296
        .value_kind:     by_value
      - .offset:         296
        .size:           4
        .value_kind:     hidden_block_count_x
      - .offset:         300
        .size:           4
        .value_kind:     hidden_block_count_y
      - .offset:         304
        .size:           4
        .value_kind:     hidden_block_count_z
      - .offset:         308
        .size:           2
        .value_kind:     hidden_group_size_x
      - .offset:         310
        .size:           2
        .value_kind:     hidden_group_size_y
      - .offset:         312
        .size:           2
        .value_kind:     hidden_group_size_z
      - .offset:         314
        .size:           2
        .value_kind:     hidden_remainder_x
      - .offset:         316
        .size:           2
        .value_kind:     hidden_remainder_y
      - .offset:         318
        .size:           2
        .value_kind:     hidden_remainder_z
      - .offset:         336
        .size:           8
        .value_kind:     hidden_global_offset_x
      - .offset:         344
        .size:           8
        .value_kind:     hidden_global_offset_y
      - .offset:         352
        .size:           8
        .value_kind:     hidden_global_offset_z
      - .offset:         360
        .size:           2
        .value_kind:     hidden_grid_dims
      - .offset:         384
        .size:           8
        .value_kind:     hidden_multigrid_sync_arg
      - .offset:         416
        .size:           4
        .value_kind:     hidden_dynamic_lds_size
    .group_segment_fixed_size: 0
    .kernarg_segment_align: 8
    .kernarg_segment_size: 552
    .language:       OpenCL C
    .language_version:
      - 2
      - 0
    .max_flat_workgroup_size: 512
    .name:           _Z8mega_fwd4Args
    .private_segment_fixed_size: 0
    .sgpr_count:     108
    .sgpr_spill_count: 57
    .symbol:         _Z8mega_fwd4Args.kd
    .uniform_work_group_size: 1
    .uses_dynamic_stack: false
    .vgpr_count:     255
    .vgpr_spill_count: 0
    .wavefront_size: 64
